# one static s_setprio 1 for waves 4-7 at kernel entry (on top of the early first LDS-DMA piece)
# speedup vs baseline: 1.0067x; 1.0067x over previous
_Z11mega_kernel6Paramsii:
	s_load_dwordx2 s[34:35], s[0:1], 0x130
	s_load_dwordx4 s[76:79], s[0:1], 0x120
	s_load_dwordx8 s[24:31], s[0:1], 0x100
	s_load_dword s92, s[0:1], 0x148
	s_load_dwordx2 s[82:83], s[0:1], 0x140
	s_add_u32 s4, s0, 0x140
	s_addc_u32 s5, s1, 0
	v_and_b32_e32 v181, 0x3ff, v0
	s_nop 1
	v_readfirstlane_b32 s32, v181
	s_nop 3
	s_lshr_b32 s32, s32, 6
	s_cmp_ge_u32 s32, 4
	s_cbranch_scc0 .Lprio_half_done
	s_setprio 1
.Lprio_half_done:
	v_writelane_b32 v252, s4, 0
	v_cmp_eq_u32_e64 s[94:95], 0, v181
	s_nop 0
	v_writelane_b32 v252, s5, 1
	s_and_saveexec_b64 s[4:5], s[94:95]
	s_cbranch_execz .LBB0_2
	s_add_i32 s3, 0, 0x24800
	v_mov_b32_e32 v1, 0
	v_mov_b32_e32 v2, s3
	s_add_i32 s3, 0, 0x24804
	ds_write_b32 v2, v1
	v_mov_b32_e32 v2, s3
	ds_write_b32 v2, v1
